# GEMM unit headers: removed the redundant second zeroing of the 128 accumulators (they were zeroed twice per tile)
# speedup vs baseline: 1.0113x; 1.0049x over previous
; template <class Epi, class Sched, bool ALIGN_EPI = false, bool SP2 = false>
; __device__ __forceinline__ void gemm_phase(PG8_LAS unsigned char* lds, const Gemm g, const Sched& S, const Epi& E) {
;     ...
;         for (int t = 0; t < nt; t += 2) {
;             const bool last = (t == nt - 2);
;             const char* a1 = cA + (size_t)(t + 1) * kstep;
;             const char* a2 = last ? nA : cA + (size_t)(t + 2) * kstep; const char* b2 = last ? nB : cB + (size_t)(t + 2) * kstep;
;     ...
; #pragma unroll
;         for (int a = 0; a < 2; ++a)
; #pragma unroll
;             for (int b = 0; b < 2; ++b)
; #pragma unroll
;                 for (int m = 0; m < 4; ++m)
; #pragma unroll
;                     for (int n = 0; n < 2; ++n) acc[a][b][m][n] = (f32x4){0.f, 0.f, 0.f, 0.f};
;         cur = nxt; cA = nA; cB = nB; ++ui;
.LBB0_714:
	v_mov_b32_e32 v127, 0
	s_andn2_b64 vcc, exec, s[72:73]
	v_mov_b32_e32 v126, v127
	v_mov_b32_e32 v125, v127
	v_mov_b32_e32 v124, v127
	v_mov_b32_e32 v123, v127
	v_mov_b32_e32 v122, v127
	v_mov_b32_e32 v121, v127
	v_mov_b32_e32 v120, v127
	v_mov_b32_e32 v111, v127
	v_mov_b32_e32 v110, v127
	v_mov_b32_e32 v109, v127
	v_mov_b32_e32 v108, v127
	v_mov_b32_e32 v107, v127
	v_mov_b32_e32 v106, v127
	v_mov_b32_e32 v105, v127
	v_mov_b32_e32 v104, v127
	v_mov_b32_e32 v95, v127
	s_waitcnt vmcnt(0)
	v_mov_b32_e32 v94, v127
	v_mov_b32_e32 v93, v127
	v_mov_b32_e32 v92, v127
	v_mov_b32_e32 v91, v127
	v_mov_b32_e32 v90, v127
	v_mov_b32_e32 v89, v127
	v_mov_b32_e32 v88, v127
	v_mov_b32_e32 v79, v127
	s_waitcnt lgkmcnt(0)
	v_mov_b32_e32 v78, v127
	v_mov_b32_e32 v77, v127
	v_mov_b32_e32 v76, v127
	v_mov_b32_e32 v75, v127
	v_mov_b32_e32 v74, v127
	v_mov_b32_e32 v73, v127
	v_mov_b32_e32 v72, v127
	v_mov_b32_e32 v119, v127
	v_mov_b32_e32 v118, v127
	v_mov_b32_e32 v117, v127
	v_mov_b32_e32 v116, v127
	v_mov_b32_e32 v115, v127
	v_mov_b32_e32 v114, v127
	v_mov_b32_e32 v113, v127
	v_mov_b32_e32 v112, v127
	v_mov_b32_e32 v103, v127
	v_mov_b32_e32 v102, v127
	v_mov_b32_e32 v101, v127
	v_mov_b32_e32 v100, v127
	v_mov_b32_e32 v99, v127
	v_mov_b32_e32 v98, v127
	v_mov_b32_e32 v97, v127
	v_mov_b32_e32 v96, v127
	v_mov_b32_e32 v87, v127
	v_mov_b32_e32 v86, v127
	v_mov_b32_e32 v85, v127
	v_mov_b32_e32 v84, v127
	v_mov_b32_e32 v83, v127
	v_mov_b32_e32 v82, v127
	v_mov_b32_e32 v81, v127
	v_mov_b32_e32 v80, v127
	v_mov_b32_e32 v71, v127
	v_mov_b32_e32 v70, v127
	v_mov_b32_e32 v69, v127
	v_mov_b32_e32 v68, v127
	v_mov_b32_e32 v67, v127
	v_mov_b32_e32 v66, v127
	v_mov_b32_e32 v65, v127
	v_mov_b32_e32 v64, v127
	v_mov_b32_e32 v63, v127
	v_mov_b32_e32 v62, v127
	v_mov_b32_e32 v61, v127
	v_mov_b32_e32 v60, v127
	v_mov_b32_e32 v59, v127
	v_mov_b32_e32 v58, v127
	v_mov_b32_e32 v57, v127
	v_mov_b32_e32 v56, v127
	v_mov_b32_e32 v47, v127
	v_mov_b32_e32 v46, v127
	v_mov_b32_e32 v45, v127
	v_mov_b32_e32 v44, v127
	v_mov_b32_e32 v43, v127
	v_mov_b32_e32 v42, v127
	v_mov_b32_e32 v41, v127
	v_mov_b32_e32 v40, v127
	v_mov_b32_e32 v31, v127
	v_mov_b32_e32 v30, v127
	v_mov_b32_e32 v29, v127
	v_mov_b32_e32 v28, v127
	v_mov_b32_e32 v27, v127
	v_mov_b32_e32 v26, v127
	v_mov_b32_e32 v25, v127
	v_mov_b32_e32 v24, v127
	v_mov_b32_e32 v15, v127
	v_mov_b32_e32 v14, v127
	v_mov_b32_e32 v13, v127
	v_mov_b32_e32 v12, v127
	v_mov_b32_e32 v11, v127
	v_mov_b32_e32 v10, v127
	v_mov_b32_e32 v9, v127
	v_mov_b32_e32 v8, v127
	v_mov_b32_e32 v55, v127
	v_mov_b32_e32 v54, v127
	v_mov_b32_e32 v53, v127
	v_mov_b32_e32 v52, v127
	v_mov_b32_e32 v51, v127
	v_mov_b32_e32 v50, v127
	v_mov_b32_e32 v49, v127
	v_mov_b32_e32 v48, v127
	v_mov_b32_e32 v39, v127
	v_mov_b32_e32 v38, v127
	v_mov_b32_e32 v37, v127
	v_mov_b32_e32 v36, v127
	v_mov_b32_e32 v35, v127
	v_mov_b32_e32 v34, v127
	v_mov_b32_e32 v33, v127
	v_mov_b32_e32 v32, v127
	v_mov_b32_e32 v23, v127
	v_mov_b32_e32 v22, v127
	v_mov_b32_e32 v21, v127
	v_mov_b32_e32 v20, v127
	v_mov_b32_e32 v19, v127
	v_mov_b32_e32 v18, v127
	v_mov_b32_e32 v17, v127
	v_mov_b32_e32 v16, v127
	v_mov_b32_e32 v7, v127
	v_mov_b32_e32 v6, v127
	v_mov_b32_e32 v5, v127
	v_mov_b32_e32 v4, v127
	v_mov_b32_e32 v3, v127
	v_mov_b32_e32 v2, v127
	v_mov_b32_e32 v1, v127
	v_mov_b32_e32 v0, v127
	s_cbranch_vccnz .LBB0_717
	s_add_u32 s0, s46, 0x80
	s_addc_u32 s1, s47, 0
	s_add_u32 s20, s44, 0x100
	s_addc_u32 s21, s45, 0
	s_mov_b32 s28, 0

; template <class Epi, class Sched, bool ALIGN_EPI = false, bool SP2 = false>
; __device__ __forceinline__ void gemm_phase(PG8_LAS unsigned char* lds, const Gemm g, const Sched& S, const Epi& E) {
;     ...
;         for (int t = 0; t < nt; t += 2) {
;             const bool last = (t == nt - 2);
;             const char* a1 = cA + (size_t)(t + 1) * kstep;
;             const char* a2 = last ? nA : cA + (size_t)(t + 2) * kstep; const char* b2 = last ? nB : cB + (size_t)(t + 2) * kstep;
;     ...
; #pragma unroll
;         for (int a = 0; a < 2; ++a)
; #pragma unroll
;             for (int b = 0; b < 2; ++b)
; #pragma unroll
;                 for (int m = 0; m < 4; ++m)
; #pragma unroll
;                     for (int n = 0; n < 2; ++n) acc[a][b][m][n] = (f32x4){0.f, 0.f, 0.f, 0.f};
;         cur = nxt; cA = nA; cB = nB; ++ui;
.LBB0_1047:
	v_mov_b32_e32 v123, 0
	s_andn2_b64 vcc, exec, s[72:73]
	v_mov_b32_e32 v122, v123
	v_mov_b32_e32 v121, v123
	v_mov_b32_e32 v120, v123
	v_mov_b32_e32 v127, v123
	v_mov_b32_e32 v126, v123
	v_mov_b32_e32 v125, v123
	v_mov_b32_e32 v124, v123
	v_mov_b32_e32 v111, v123
	v_mov_b32_e32 v110, v123
	v_mov_b32_e32 v109, v123
	v_mov_b32_e32 v108, v123
	v_mov_b32_e32 v107, v123
	v_mov_b32_e32 v106, v123
	v_mov_b32_e32 v105, v123
	v_mov_b32_e32 v104, v123
	v_mov_b32_e32 v95, v123
	s_waitcnt vmcnt(0)
	v_mov_b32_e32 v94, v123
	v_mov_b32_e32 v93, v123
	v_mov_b32_e32 v92, v123
	v_mov_b32_e32 v91, v123
	v_mov_b32_e32 v90, v123
	v_mov_b32_e32 v89, v123
	v_mov_b32_e32 v88, v123
	v_mov_b32_e32 v79, v123
	v_mov_b32_e32 v78, v123
	v_mov_b32_e32 v77, v123
	v_mov_b32_e32 v76, v123
	v_mov_b32_e32 v75, v123
	v_mov_b32_e32 v74, v123
	v_mov_b32_e32 v73, v123
	v_mov_b32_e32 v72, v123
	v_mov_b32_e32 v119, v123
	v_mov_b32_e32 v118, v123
	v_mov_b32_e32 v117, v123
	v_mov_b32_e32 v116, v123
	v_mov_b32_e32 v115, v123
	v_mov_b32_e32 v114, v123
	v_mov_b32_e32 v113, v123
	v_mov_b32_e32 v112, v123
	v_mov_b32_e32 v103, v123
	v_mov_b32_e32 v102, v123
	v_mov_b32_e32 v101, v123
	v_mov_b32_e32 v100, v123
	v_mov_b32_e32 v99, v123
	v_mov_b32_e32 v98, v123
	v_mov_b32_e32 v97, v123
	v_mov_b32_e32 v96, v123
	v_mov_b32_e32 v87, v123
	v_mov_b32_e32 v86, v123
	v_mov_b32_e32 v85, v123
	v_mov_b32_e32 v84, v123
	v_mov_b32_e32 v83, v123
	v_mov_b32_e32 v82, v123
	v_mov_b32_e32 v81, v123
	v_mov_b32_e32 v80, v123
	v_mov_b32_e32 v71, v123
	v_mov_b32_e32 v70, v123
	v_mov_b32_e32 v69, v123
	v_mov_b32_e32 v68, v123
	v_mov_b32_e32 v67, v123
	v_mov_b32_e32 v66, v123
	v_mov_b32_e32 v65, v123
	v_mov_b32_e32 v64, v123
	v_mov_b32_e32 v63, v123
	v_mov_b32_e32 v62, v123
	v_mov_b32_e32 v61, v123
	v_mov_b32_e32 v60, v123
	v_mov_b32_e32 v59, v123
	v_mov_b32_e32 v58, v123
	v_mov_b32_e32 v57, v123
	v_mov_b32_e32 v56, v123
	v_mov_b32_e32 v47, v123
	v_mov_b32_e32 v46, v123
	v_mov_b32_e32 v45, v123
	v_mov_b32_e32 v44, v123
	v_mov_b32_e32 v43, v123
	v_mov_b32_e32 v42, v123
	v_mov_b32_e32 v41, v123
	v_mov_b32_e32 v40, v123
	v_mov_b32_e32 v31, v123
	v_mov_b32_e32 v30, v123
	v_mov_b32_e32 v29, v123
	v_mov_b32_e32 v28, v123
	v_mov_b32_e32 v27, v123
	v_mov_b32_e32 v26, v123
	v_mov_b32_e32 v25, v123
	v_mov_b32_e32 v24, v123
	v_mov_b32_e32 v15, v123
	v_mov_b32_e32 v14, v123
	v_mov_b32_e32 v13, v123
	v_mov_b32_e32 v12, v123
	v_mov_b32_e32 v11, v123
	v_mov_b32_e32 v10, v123
	v_mov_b32_e32 v9, v123
	v_mov_b32_e32 v8, v123
	v_mov_b32_e32 v55, v123
	v_mov_b32_e32 v54, v123
	v_mov_b32_e32 v53, v123
	v_mov_b32_e32 v52, v123
	v_mov_b32_e32 v51, v123
	v_mov_b32_e32 v50, v123
	v_mov_b32_e32 v49, v123
	v_mov_b32_e32 v48, v123
	v_mov_b32_e32 v39, v123
	v_mov_b32_e32 v38, v123
	v_mov_b32_e32 v37, v123
	v_mov_b32_e32 v36, v123
	v_mov_b32_e32 v35, v123
	v_mov_b32_e32 v34, v123
	v_mov_b32_e32 v33, v123
	v_mov_b32_e32 v32, v123
	v_mov_b32_e32 v23, v123
	v_mov_b32_e32 v22, v123
	v_mov_b32_e32 v21, v123
	v_mov_b32_e32 v20, v123
	v_mov_b32_e32 v19, v123
	v_mov_b32_e32 v18, v123
	v_mov_b32_e32 v17, v123
	v_mov_b32_e32 v16, v123
	v_mov_b32_e32 v7, v123
	v_mov_b32_e32 v6, v123
	v_mov_b32_e32 v5, v123
	v_mov_b32_e32 v4, v123
	v_mov_b32_e32 v3, v123
	v_mov_b32_e32 v2, v123
	v_mov_b32_e32 v1, v123
	v_mov_b32_e32 v0, v123
	s_cbranch_vccnz .LBB0_1050
	s_add_u32 s42, s42, 0x80
	s_addc_u32 s43, s43, 0
	s_add_u32 s57, s44, 0x100
	s_addc_u32 s58, s45, 0
	s_mov_b32 s44, 0

; template <class Epi, class Sched, bool ALIGN_EPI = false, bool SP2 = false>
; __device__ __forceinline__ void gemm_phase(PG8_LAS unsigned char* lds, const Gemm g, const Sched& S, const Epi& E) {
;     ...
;         for (int t = 0; t < nt; t += 2) {
;             const bool last = (t == nt - 2);
;             const char* a1 = cA + (size_t)(t + 1) * kstep;
;             const char* a2 = last ? nA : cA + (size_t)(t + 2) * kstep; const char* b2 = last ? nB : cB + (size_t)(t + 2) * kstep;
;     ...
; #pragma unroll
;         for (int a = 0; a < 2; ++a)
; #pragma unroll
;             for (int b = 0; b < 2; ++b)
; #pragma unroll
;                 for (int m = 0; m < 4; ++m)
; #pragma unroll
;                     for (int n = 0; n < 2; ++n) acc[a][b][m][n] = (f32x4){0.f, 0.f, 0.f, 0.f};
;         cur = nxt; cA = nA; cB = nB; ++ui;
.LBB0_1166:
	v_mov_b32_e32 v123, 0
	s_andn2_b64 vcc, exec, s[72:73]
	v_mov_b32_e32 v122, v123
	v_mov_b32_e32 v121, v123
	v_mov_b32_e32 v120, v123
	v_mov_b32_e32 v115, v123
	v_mov_b32_e32 v114, v123
	v_mov_b32_e32 v113, v123
	v_mov_b32_e32 v112, v123
	v_mov_b32_e32 v107, v123
	v_mov_b32_e32 v106, v123
	v_mov_b32_e32 v105, v123
	v_mov_b32_e32 v104, v123
	v_mov_b32_e32 v99, v123
	s_waitcnt vmcnt(0)
	v_mov_b32_e32 v98, v123
	v_mov_b32_e32 v97, v123
	v_mov_b32_e32 v96, v123
	v_mov_b32_e32 v91, v123
	v_mov_b32_e32 v90, v123
	v_mov_b32_e32 v89, v123
	v_mov_b32_e32 v88, v123
	v_mov_b32_e32 v83, v123
	v_mov_b32_e32 v82, v123
	v_mov_b32_e32 v81, v123
	v_mov_b32_e32 v80, v123
	v_mov_b32_e32 v75, v123
	v_mov_b32_e32 v74, v123
	v_mov_b32_e32 v73, v123
	v_mov_b32_e32 v72, v123
	v_mov_b32_e32 v67, v123
	v_mov_b32_e32 v66, v123
	v_mov_b32_e32 v65, v123
	v_mov_b32_e32 v64, v123
	v_mov_b32_e32 v127, v123
	v_mov_b32_e32 v126, v123
	v_mov_b32_e32 v125, v123
	v_mov_b32_e32 v124, v123
	v_mov_b32_e32 v119, v123
	v_mov_b32_e32 v118, v123
	v_mov_b32_e32 v117, v123
	v_mov_b32_e32 v116, v123
	v_mov_b32_e32 v111, v123
	v_mov_b32_e32 v110, v123
	v_mov_b32_e32 v109, v123
	v_mov_b32_e32 v108, v123
	v_mov_b32_e32 v103, v123
	v_mov_b32_e32 v102, v123
	v_mov_b32_e32 v101, v123
	v_mov_b32_e32 v100, v123
	v_mov_b32_e32 v95, v123
	v_mov_b32_e32 v94, v123
	v_mov_b32_e32 v93, v123
	v_mov_b32_e32 v92, v123
	v_mov_b32_e32 v87, v123
	v_mov_b32_e32 v86, v123
	v_mov_b32_e32 v85, v123
	v_mov_b32_e32 v84, v123
	v_mov_b32_e32 v79, v123
	v_mov_b32_e32 v78, v123
	v_mov_b32_e32 v77, v123
	v_mov_b32_e32 v76, v123
	v_mov_b32_e32 v71, v123
	v_mov_b32_e32 v70, v123
	v_mov_b32_e32 v69, v123
	v_mov_b32_e32 v68, v123
	v_mov_b32_e32 v59, v123
	v_mov_b32_e32 v58, v123
	v_mov_b32_e32 v57, v123
	v_mov_b32_e32 v56, v123
	v_mov_b32_e32 v51, v123
	v_mov_b32_e32 v50, v123
	v_mov_b32_e32 v49, v123
	v_mov_b32_e32 v48, v123
	v_mov_b32_e32 v43, v123
	v_mov_b32_e32 v42, v123
	v_mov_b32_e32 v41, v123
	v_mov_b32_e32 v40, v123
	v_mov_b32_e32 v35, v123
	v_mov_b32_e32 v34, v123
	v_mov_b32_e32 v33, v123
	v_mov_b32_e32 v32, v123
	v_mov_b32_e32 v27, v123
	v_mov_b32_e32 v26, v123
	v_mov_b32_e32 v25, v123
	v_mov_b32_e32 v24, v123
	v_mov_b32_e32 v19, v123
	v_mov_b32_e32 v18, v123
	v_mov_b32_e32 v17, v123
	v_mov_b32_e32 v16, v123
	v_mov_b32_e32 v11, v123
	v_mov_b32_e32 v10, v123
	v_mov_b32_e32 v9, v123
	v_mov_b32_e32 v8, v123
	v_mov_b32_e32 v7, v123
	v_mov_b32_e32 v6, v123
	v_mov_b32_e32 v5, v123
	v_mov_b32_e32 v4, v123
	v_mov_b32_e32 v63, v123
	v_mov_b32_e32 v62, v123
	v_mov_b32_e32 v61, v123
	v_mov_b32_e32 v60, v123
	v_mov_b32_e32 v55, v123
	v_mov_b32_e32 v54, v123
	v_mov_b32_e32 v53, v123
	v_mov_b32_e32 v52, v123
	v_mov_b32_e32 v47, v123
	v_mov_b32_e32 v46, v123
	v_mov_b32_e32 v45, v123
	v_mov_b32_e32 v44, v123
	v_mov_b32_e32 v39, v123
	v_mov_b32_e32 v38, v123
	v_mov_b32_e32 v37, v123
	v_mov_b32_e32 v36, v123
	v_mov_b32_e32 v31, v123
	v_mov_b32_e32 v30, v123
	v_mov_b32_e32 v29, v123
	v_mov_b32_e32 v28, v123
	v_mov_b32_e32 v23, v123
	v_mov_b32_e32 v22, v123
	v_mov_b32_e32 v21, v123
	v_mov_b32_e32 v20, v123
	v_mov_b32_e32 v15, v123
	v_mov_b32_e32 v14, v123
	v_mov_b32_e32 v13, v123
	v_mov_b32_e32 v12, v123
	v_mov_b32_e32 v3, v123
	v_mov_b32_e32 v2, v123
	v_mov_b32_e32 v1, v123
	v_mov_b32_e32 v0, v123
	s_cbranch_vccnz .LBB0_1169
	s_add_u32 s4, s4, 0x80
	s_addc_u32 s5, s5, 0
	s_add_u32 s20, s22, 0x100
	s_addc_u32 s21, s23, 0
	s_mov_b32 s22, 0
